# c55 with the memory-KV projection K-loop head placed at byte offset 4 mod 64 like the in-projection loop (cold-path padding only, other loop offsets unchanged)
# speedup vs baseline: 1.0077x; 1.0077x over previous
; DI unsigned cvt_pk_bf16(float lo, float hi) { const f32x2_t v = {lo, hi}; const bf16v2_t b = __builtin_convertvector(v, bf16v2_t); return __builtin_bit_cast(unsigned, b); }
; DI float bf_lo(unsigned u) { return __uint_as_float(u << 16); }
; DI float bf_hi(unsigned u) { return __uint_as_float(u & 0xffff0000u); }
; template <bool OUT_BF>
; DI void norm_rows_bf(const bf16_t* src, const float* w, void* dst, int nrows, int lane, int gw, int nw) {
;     ...
;     for (int rb = gw; rb < nrows; rb += 4 * nw) {
;         u32x4 a[4][2];
; #pragma unroll
;         for (int q = 0; q < 4; ++q) { const int r = rb + q * nw; const bf16_t* sp = src + (size_t)(r < nrows ? r : rb) * 1024;
;             a[q][0] = *(const u32x4*)(sp + lane * 8); a[q][1] = *(const u32x4*)(sp + 512 + lane * 8); }
; #pragma unroll
;         for (int q = 0; q < 4; ++q) {
;             const int r = rb + q * nw;
;             float v[16]; float ss = 0.f;
; #pragma unroll
;             for (int i = 0; i < 2; ++i)
; #pragma unroll
;                 for (int e = 0; e < 4; ++e) { v[8 * i + 2 * e] = bf_lo(a[q][i][e]); v[8 * i + 2 * e + 1] = bf_hi(a[q][i][e]); }
; #pragma unroll
;             for (int e = 0; e < 16; ++e) ss += v[e] * v[e];
;             ss = wave_sum(ss);
;             const float rs = rsqrtf(ss * (1.0f / 1024.0f) + 1e-6f);
;             if (r < nrows) {
; #pragma unroll
;                 for (int i = 0; i < 2; ++i) {
;                     float y[8];
; #pragma unroll
;                     for (int e = 0; e < 8; ++e) y[e] = v[8 * i + e] * rs * wv[2 * i + (e >> 2)][e & 3];
;                     if (OUT_BF) { u32x4 o; o.x = cvt_pk_bf16(y[0], y[1]); o.y = cvt_pk_bf16(y[2], y[3]); o.z = cvt_pk_bf16(y[4], y[5]); o.w = cvt_pk_bf16(y[6], y[7]);
;                         *(u32x4*)((bf16_t*)dst + (size_t)r * 1024 + i * 512 + lane * 8) = o; }
;                     else { float* d = (float*)dst + (size_t)r * 1024 + i * 512 + lane * 8; *(f32x4*)d = (f32x4){y[0], y[1], y[2], y[3]}; *(f32x4*)(d + 4) = (f32x4){y[4], y[5], y[6], y[7]}; }
;                 }
;             }
;         }
.LBB0_66:
	s_waitcnt vmcnt(3)
	s_nop 0
	v_lshlrev_b32_e32 v26, 16, v22
	v_and_b32_e32 v27, 0xffff0000, v22
	v_lshlrev_b32_e32 v28, 16, v23
	v_and_b32_e32 v29, 0xffff0000, v23
	v_pk_mul_f32 v[40:41], v[26:27], v[26:27]
	v_pk_mul_f32 v[42:43], v[28:29], v[28:29]
	v_add_f32_e32 v13, v40, v41
	v_lshlrev_b32_e32 v34, 16, v24
	v_and_b32_e32 v35, 0xffff0000, v24
	v_add_f32_e32 v13, v42, v13
	v_pk_mul_f32 v[44:45], v[34:35], v[34:35]
	v_add_f32_e32 v13, v43, v13
	v_lshlrev_b32_e32 v36, 16, v25
	v_and_b32_e32 v37, 0xffff0000, v25
	v_add_f32_e32 v13, v44, v13
	v_pk_mul_f32 v[46:47], v[36:37], v[36:37]
	v_add_f32_e32 v13, v45, v13
	s_waitcnt vmcnt(2)
	v_lshlrev_b32_e32 v22, 16, v18
	v_and_b32_e32 v23, 0xffff0000, v18
	v_add_f32_e32 v13, v46, v13
	s_waitcnt lgkmcnt(0)
	v_pk_mul_f32 v[48:49], v[22:23], v[22:23]
	v_add_f32_e32 v13, v47, v13
	v_lshlrev_b32_e32 v18, 16, v19
	v_and_b32_e32 v19, 0xffff0000, v19
	v_add_f32_e32 v13, v48, v13
	v_pk_mul_f32 v[50:51], v[18:19], v[18:19]
	v_add_f32_e32 v13, v49, v13
	v_lshlrev_b32_e32 v24, 16, v20
	v_and_b32_e32 v25, 0xffff0000, v20
	v_add_f32_e32 v13, v50, v13
	v_pk_mul_f32 v[52:53], v[24:25], v[24:25]
	v_add_f32_e32 v13, v51, v13
	v_lshlrev_b32_e32 v20, 16, v21
	v_and_b32_e32 v21, 0xffff0000, v21
	v_add_f32_e32 v13, v52, v13
	v_pk_mul_f32 v[54:55], v[20:21], v[20:21]
	v_add_f32_e32 v13, v53, v13
	v_add_f32_e32 v13, v54, v13
	v_add_f32_e32 v13, v55, v13
	ds_bpermute_b32 v40, v33, v13
	s_andn2_b64 vcc, exec, s[38:39]
	s_waitcnt lgkmcnt(0)
	v_add_f32_e32 v13, v13, v40
	ds_bpermute_b32 v40, v56, v13
	s_waitcnt lgkmcnt(0)
	v_add_f32_e32 v13, v13, v40
	ds_bpermute_b32 v40, v57, v13
	s_waitcnt lgkmcnt(0)
	v_add_f32_e32 v13, v13, v40
	ds_bpermute_b32 v40, v58, v13
	s_waitcnt lgkmcnt(0)
	v_add_f32_e32 v13, v13, v40
	ds_bpermute_b32 v40, v59, v13
	s_waitcnt lgkmcnt(0)
	v_add_f32_e32 v13, v13, v40
	ds_bpermute_b32 v40, v60, v13
	s_cbranch_vccnz .LBB0_61
	s_waitcnt lgkmcnt(0)
	v_add_f32_e32 v13, v13, v40
	v_fmamk_f32 v13, v13, 0x3a800000, v231
	v_cmp_gt_f32_e32 vcc, s33, v13
	v_mul_f32_e32 v40, 0x4b800000, v13
	s_ashr_i32 s37, s36, 31
	v_cndmask_b32_e32 v13, v13, v40, vcc
	v_rsq_f32_e32 v13, v13
	s_lshl_b64 s[14:15], s[36:37], 11
	v_lshl_add_u64 v[42:43], v[30:31], 0, s[14:15]
	v_mul_f32_e32 v40, 0x45800000, v13
	v_cndmask_b32_e32 v40, v13, v40, vcc
	v_pk_mul_f32 v[26:27], v[40:41], v[26:27] op_sel_hi:[0,1]
	v_pk_mul_f32 v[28:29], v[40:41], v[28:29] op_sel_hi:[0,1]
	v_pk_mul_f32 v[34:35], v[40:41], v[34:35] op_sel_hi:[0,1]
	v_pk_mul_f32 v[36:37], v[40:41], v[36:37] op_sel_hi:[0,1]
	v_pk_mul_f32 v[26:27], v[4:5], v[26:27]
	v_pk_mul_f32 v[28:29], v[6:7], v[28:29]
	v_pk_mul_f32 v[34:35], v[14:15], v[34:35]
	v_pk_mul_f32 v[36:37], v[16:17], v[36:37]
	v_cvt_pk_bf16_f32 v26, v26, v27
	v_cvt_pk_bf16_f32 v27, v28, v29
	v_cvt_pk_bf16_f32 v28, v34, v35
	v_cvt_pk_bf16_f32 v29, v36, v37
	v_pk_mul_f32 v[18:19], v[40:41], v[18:19] op_sel_hi:[0,1]
	global_store_dwordx4 v[42:43], v[26:29], off
	v_pk_mul_f32 v[22:23], v[40:41], v[22:23] op_sel_hi:[0,1]
	v_pk_mul_f32 v[22:23], v[8:9], v[22:23]
	v_pk_mul_f32 v[26:27], v[10:11], v[18:19]
	v_pk_mul_f32 v[18:19], v[40:41], v[24:25] op_sel_hi:[0,1]
	v_pk_mul_f32 v[24:25], v[0:1], v[18:19]
	v_pk_mul_f32 v[18:19], v[40:41], v[20:21] op_sel_hi:[0,1]
	v_pk_mul_f32 v[28:29], v[2:3], v[18:19]
	v_cvt_pk_bf16_f32 v18, v22, v23
	v_cvt_pk_bf16_f32 v19, v26, v27
	v_cvt_pk_bf16_f32 v20, v24, v25
	v_cvt_pk_bf16_f32 v21, v28, v29
	global_store_dwordx4 v[42:43], v[18:21], off offset:1024
	s_branch .LBB0_61
	s_nop 0

; #define LAS __attribute__((address_space(3)))
; DI void tok0_mix_dil(ldsp lds, const Params& p, const float* P, float* BRo, int task, int tid, int wid, int lane) {
;     const int b = task >> 2, hm = task & 3;
;     const float* pr = P + (size_t)b * 8192;
;     LAS float* OUT = (LAS float*)(lds + 65536); LAS float* S18 = OUT + 64;
;     tok0_mem(lds, pr + DB_QM + hm * 64, p.mem + (size_t)b * 256 * 1024, p.mem_norm_w, p.w_memkv + (size_t)1024 * 512, hm, OUT, tid, wid, lane);
; __global__ void __launch_bounds__(NTHREADS, 2) megak(Params p) {
;     ...
;             if (L == 0) {
;                 __syncthreads();
;                 for (int t = blockIdx.x; t < BATCH * 4; t += gridDim.x) tok0_mix_dil(lds, p, T0P, T0BR, t, tid, wid, lane);
.LBB0_91:
	s_andn2_b64 vcc, exec, s[40:41]
	s_cbranch_vccnz .LBB0_126
	v_readlane_b32 s14, v251, 45
	v_readlane_b32 s15, v251, 46
	s_andn2_b64 vcc, exec, s[14:15]
	s_waitcnt vmcnt(0) lgkmcnt(0)
	s_barrier
	s_cbranch_vccnz .LBB0_126
	v_mov_b32_e32 v33, v12
	v_mov_b64_e32 v[30:31], v[32:33]
	v_ashrrev_i32_e32 v33, 31, v32
	v_lshlrev_b64 v[0:1], 11, v[32:33]
	s_mov_b64 s[14:15], 0x100000
	v_lshl_add_u64 v[78:79], v[0:1], 0, s[14:15]
	v_and_b32_e32 v0, 64, v233
	v_add_u32_e32 v0, 64, v0
	v_xor_b32_e32 v1, 32, v233
	v_cmp_lt_i32_e32 vcc, v1, v0
	s_lshl_b32 s22, s16, 5
	v_readlane_b32 s0, v255, 14
	v_cndmask_b32_e32 v1, v233, v1, vcc
	v_lshlrev_b32_e32 v95, 2, v1
	v_xor_b32_e32 v1, 16, v233
	v_cmp_lt_i32_e32 vcc, v1, v0
	s_cmp_lt_u32 s0, 64
	v_lshlrev_b32_e32 v3, 2, v32
	v_cndmask_b32_e32 v1, v233, v1, vcc
	v_lshlrev_b32_e32 v96, 2, v1
	v_xor_b32_e32 v1, 8, v233
	v_cmp_lt_i32_e32 vcc, v1, v0
	v_readlane_b32 s48, v254, 15
	s_cselect_b64 s[46:47], -1, 0
	v_cndmask_b32_e32 v1, v233, v1, vcc
	v_lshlrev_b32_e32 v97, 2, v1
	v_xor_b32_e32 v1, 4, v233
	v_cmp_lt_i32_e32 vcc, v1, v0
	s_add_i32 s0, 0, 0x10000
	v_readlane_b32 s49, v254, 16
	v_cndmask_b32_e32 v1, v233, v1, vcc
	v_lshlrev_b32_e32 v98, 2, v1
	v_xor_b32_e32 v1, 2, v233
	v_cmp_lt_i32_e32 vcc, v1, v0
	v_add_u32_e32 v102, s0, v3
	s_cmp_lt_i32 s16, 18
	v_cndmask_b32_e32 v1, v233, v1, vcc
	v_lshlrev_b32_e32 v99, 2, v1
	v_xor_b32_e32 v1, 1, v233
	v_cmp_lt_i32_e32 vcc, v1, v0
	s_movk_i32 s0, 0x300
	v_lshlrev_b32_e32 v4, 4, v32
	v_cndmask_b32_e32 v0, v233, v1, vcc
	v_ashrrev_i32_e32 v1, 8, v32
	v_lshlrev_b32_e32 v100, 2, v0
	v_lshlrev_b32_e32 v0, 7, v1
	s_cselect_b64 s[48:49], -1, 0
	v_cmp_gt_i32_e64 s[42:43], s0, v32
	s_add_i32 s0, 0, 0x1000
	v_lshlrev_b32_e32 v2, 12, v1
	v_and_b32_e32 v4, 0xff0, v4
	v_ashrrev_i32_e32 v7, 4, v32
	s_lshl_b32 s14, s16, 7
	s_ashr_i32 s23, s22, 31
	v_lshl_add_u32 v104, v1, 9, s0
	v_ashrrev_i32_e32 v1, 31, v0
	v_add_u32_e32 v13, 0, v3
	v_add3_u32 v101, 0, v2, v4
	v_lshlrev_b32_e32 v2, 5, v7
	s_add_i32 s15, s0, s14
	s_lshl_b64 s[22:23], s[22:23], 12
	v_readlane_b32 s17, v254, 14
	v_lshlrev_b64 v[0:1], 12, v[0:1]
	v_and_b32_e32 v3, 0xff, v32
	v_readlane_b32 s50, v254, 17
	v_readlane_b32 s51, v254, 18
	s_add_u32 s22, s17, s22
	v_readlane_b32 s17, v254, 31
	v_lshl_or_b32 v0, v3, 4, v0
	v_ashrrev_i32_e32 v3, 31, v2
	s_addc_u32 s23, s17, s23
	v_lshl_add_u64 v[86:87], s[50:51], 0, v[0:1]
	v_lshlrev_b64 v[0:1], 11, v[2:3]
	s_lshl_b32 s0, s16, 2
	v_lshlrev_b64 v[80:81], 2, v[32:33]
	v_readlane_b32 s52, v254, 19
	v_readlane_b32 s53, v254, 20
	v_readlane_b32 s56, v254, 23
	v_readlane_b32 s57, v254, 24
	v_lshl_add_u32 v94, v238, 4, 0
	v_mul_i32_i24_e32 v6, -12, v238
	v_lshl_add_u32 v8, v7, 8, 0
	v_lshlrev_b32_e32 v9, 4, v155
	v_lshlrev_b32_e32 v4, 4, v238
	v_mov_b32_e32 v5, v12
	v_lshl_or_b32 v0, v155, 4, v0
	s_add_i32 s17, s0, 0
	v_cmp_gt_i32_e64 s[38:39], 64, v32
	v_lshl_add_u64 v[82:83], s[52:53], 0, v[80:81]
	v_cmp_eq_u32_e64 s[40:41], 0, v238
	v_add_u32_e32 v103, 0x1f00, v32
	v_lshl_add_u64 v[84:85], s[22:23], 0, v[4:5]
	v_lshl_add_u64 v[88:89], s[56:57], 0, v[0:1]
	v_lshl_add_u32 v105, v7, 7, 0
	s_add_i32 s17, s17, 0x10100
	v_add_u32_e32 v106, v94, v6
	v_add_u32_e32 v107, v8, v9
	v_lshlrev_b32_e32 v108, 2, v238
	s_and_b32 s34, s78, 7
	s_lshl_b32 s34, s34, 4
	s_lshr_b32 s19, s78, 3
	s_or_b32 s34, s34, s19
	s_cmpk_lt_u32 s78, 0x80
	s_cselect_b32 s34, s34, s78
	s_cmpk_eq_u32 s10, 0x100
	s_cselect_b32 s34, s34, s78
	s_nop 0
	s_nop 0
	s_nop 0
	s_nop 0
	s_nop 0
	s_nop 0
	s_nop 0
	s_nop 0
	s_nop 0
	s_nop 0
	s_nop 0
	s_nop 0
	s_nop 0
	s_nop 0
	s_mov_b32 s19, s34
	v_readlane_b32 s54, v254, 21
	v_readlane_b32 s55, v254, 22
	v_readlane_b32 s58, v254, 25
	v_readlane_b32 s59, v254, 26
	v_readlane_b32 s60, v254, 27
	v_readlane_b32 s61, v254, 28
	v_readlane_b32 s62, v254, 29
	v_readlane_b32 s63, v254, 30
	s_branch .LBB0_96
	s_nop 0
	s_nop 0
	s_nop 0
	s_nop 0
	s_nop 0
	s_nop 0
	s_nop 0
	s_nop 0
	s_nop 0
	s_nop 0
	s_nop 0
	s_nop 0
	s_nop 0
	s_nop 0
	s_nop 0
